# attention epilogue: sink load hoisted to item start, output tile lane-permuted (ds_bpermute) so each store instruction touches 4x fewer rows
# speedup vs baseline: 1.0107x; 1.0029x over previous
.LBB0_95:
	s_and_b64 vcc, exec, s[2:3]
	s_cbranch_vccz .LBB0_265
	v_writelane_b32 v255, s56, 30
	v_and_b32_e32 v0, 3, v140
	v_readlane_b32 s2, v255, 12
	v_readlane_b32 s3, v255, 13
	s_and_b64 s[2:3], s[2:3], exec
	s_movk_i32 s2, 0x410
	s_cselect_b32 s15, s2, 0x400
	s_cmp_lt_i32 s57, s15
	v_writelane_b32 v255, s57, 34
	s_cselect_b64 s[2:3], -1, 0
	v_writelane_b32 v255, s2, 48
	v_bfe_u32 v147, v140, 4, 2
	v_ashrrev_i32_e32 v139, 2, v140
	v_writelane_b32 v255, s3, 49
	v_lshlrev_b32_e32 v142, 4, v0
	v_readlane_b32 s2, v255, 14
	v_readlane_b32 s3, v255, 15
	s_lshl_b32 s2, s2, 3
	s_ashr_i32 s3, s2, 31
	v_lshlrev_b32_e32 v141, 5, v0
	v_lshlrev_b32_e32 v0, 3, v140
	v_writelane_b32 v255, s2, 36
	v_bfe_u32 v156, v140, 2, 2
	s_waitcnt vmcnt(0)
	v_mul_lo_u32 v2, v139, s65
	v_lshlrev_b32_e32 v144, 2, v147
	v_and_b32_e32 v155, 24, v0
	v_writelane_b32 v255, s3, 37
	v_and_b32_e32 v145, 15, v140
	v_lshlrev_b32_e32 v146, 3, v147
	v_or_b32_e32 v154, v144, v156
	v_add_u32_e32 v143, 0, v2
	v_lshl_add_u32 v158, v147, 4, 0
	v_add_u32_e32 v157, 0, v155
	s_mov_b32 s63, 0
	v_lshlrev_b32_e32 v148, 1, v144
	v_and_b32_e32 v231, 3, v145
	v_lshlrev_b32_e32 v232, 3, v231
	v_mov_b32_e32 v233, 0
	v_bfe_u32 v230, v145, 2, 2
	v_lshl_or_b32 v230, v230, 2, v147
	v_lshl_add_u32 v231, v231, 4, v230
	v_lshlrev_b32_e32 v231, 2, v231
	v_sub_u32_e32 v230, v230, v145
	s_branch .LBB0_98

.LBB0_100:
	v_max_f32_e32 v0, v149, v149
	s_mov_b32 s10, 0x3fb8aa3b
	s_add_i32 s58, s58, s96
	s_cmp_ge_i32 s58, s15
	s_waitcnt vmcnt(0)
	v_mul_f32_e32 v9, 0x3fb8aa3b, v213
	v_max_f32_e32 v0, v0, v9
	v_sub_f32_e32 v2, v149, v0
	v_fma_f32 v0, v213, s10, -v0
	v_exp_f32_e32 v2, v2
	v_exp_f32_e32 v0, v0
	v_mov_b32_e32 v149, v1
	v_fmac_f32_e32 v0, v54, v2
	v_div_scale_f32 v3, s[2:3], v0, v0, v2
	v_rcp_f32_e32 v4, v3
	s_nop 0
	v_fma_f32 v5, -v3, v4, 1.0
	v_fmac_f32_e32 v4, v5, v4
	v_div_scale_f32 v5, vcc, v2, v0, v2
	v_mul_f32_e32 v6, v5, v4
	v_fma_f32 v7, -v3, v6, v5
	v_fmac_f32_e32 v6, v7, v4
	v_fma_f32 v3, -v3, v6, v5
	v_div_fmas_f32 v3, v3, v4, v6
	v_div_fixup_f32 v0, v3, v0, v2
	v_pk_mul_f32 v[6:7], v[50:51], v[0:1] op_sel_hi:[1,0]
	v_pk_mul_f32 v[4:5], v[52:53], v[0:1] op_sel_hi:[1,0]
	v_cvt_pk_bf16_f32 v214, v6, v7
	v_cvt_pk_bf16_f32 v215, v4, v5
	v_pk_mul_f32 v[6:7], v[46:47], v[0:1] op_sel_hi:[1,0]
	v_pk_mul_f32 v[4:5], v[48:49], v[0:1] op_sel_hi:[1,0]
	v_cvt_pk_bf16_f32 v216, v6, v7
	v_cvt_pk_bf16_f32 v217, v4, v5
	v_pk_mul_f32 v[6:7], v[42:43], v[0:1] op_sel_hi:[1,0]
	v_pk_mul_f32 v[4:5], v[44:45], v[0:1] op_sel_hi:[1,0]
	v_cvt_pk_bf16_f32 v218, v6, v7
	v_cvt_pk_bf16_f32 v219, v4, v5
	v_pk_mul_f32 v[6:7], v[38:39], v[0:1] op_sel_hi:[1,0]
	v_pk_mul_f32 v[4:5], v[40:41], v[0:1] op_sel_hi:[1,0]
	v_cvt_pk_bf16_f32 v220, v6, v7
	v_cvt_pk_bf16_f32 v221, v4, v5
	v_max_f32_e32 v0, v159, v159
	v_max_f32_e32 v0, v0, v9
	v_sub_f32_e32 v2, v159, v0
	v_fma_f32 v0, v213, s10, -v0
	v_exp_f32_e32 v2, v2
	v_exp_f32_e32 v0, v0
	s_nop 0
	v_fmac_f32_e32 v0, v34, v2
	v_div_scale_f32 v3, s[2:3], v0, v0, v2
	v_rcp_f32_e32 v4, v3
	s_nop 0
	v_fma_f32 v5, -v3, v4, 1.0
	v_fmac_f32_e32 v4, v5, v4
	v_div_scale_f32 v5, vcc, v2, v0, v2
	v_mul_f32_e32 v6, v5, v4
	v_fma_f32 v7, -v3, v6, v5
	v_fmac_f32_e32 v6, v7, v4
	v_fma_f32 v3, -v3, v6, v5
	v_div_fmas_f32 v3, v3, v4, v6
	v_div_fixup_f32 v0, v3, v0, v2
	v_pk_mul_f32 v[6:7], v[30:31], v[0:1] op_sel_hi:[1,0]
	v_pk_mul_f32 v[4:5], v[32:33], v[0:1] op_sel_hi:[1,0]
	v_cvt_pk_bf16_f32 v222, v6, v7
	v_cvt_pk_bf16_f32 v223, v4, v5
	v_pk_mul_f32 v[6:7], v[26:27], v[0:1] op_sel_hi:[1,0]
	v_pk_mul_f32 v[4:5], v[28:29], v[0:1] op_sel_hi:[1,0]
	v_cvt_pk_bf16_f32 v224, v6, v7
	v_cvt_pk_bf16_f32 v225, v4, v5
	v_pk_mul_f32 v[6:7], v[22:23], v[0:1] op_sel_hi:[1,0]
	v_pk_mul_f32 v[4:5], v[24:25], v[0:1] op_sel_hi:[1,0]
	v_cvt_pk_bf16_f32 v226, v6, v7
	v_cvt_pk_bf16_f32 v227, v4, v5
	v_pk_mul_f32 v[6:7], v[18:19], v[0:1] op_sel_hi:[1,0]
	v_pk_mul_f32 v[4:5], v[20:21], v[0:1] op_sel_hi:[1,0]
	v_cvt_pk_bf16_f32 v228, v6, v7
	v_cvt_pk_bf16_f32 v229, v4, v5
	s_nop 1
	ds_bpermute_b32 v214, v231, v214
	ds_bpermute_b32 v215, v231, v215
	ds_bpermute_b32 v216, v231, v216
	ds_bpermute_b32 v217, v231, v217
	ds_bpermute_b32 v218, v231, v218
	ds_bpermute_b32 v219, v231, v219
	ds_bpermute_b32 v220, v231, v220
	ds_bpermute_b32 v221, v231, v221
	s_waitcnt lgkmcnt(4)
	ds_bpermute_b32 v222, v231, v222
	ds_bpermute_b32 v223, v231, v223
	ds_bpermute_b32 v224, v231, v224
	ds_bpermute_b32 v225, v231, v225
	ds_bpermute_b32 v226, v231, v226
	ds_bpermute_b32 v227, v231, v227
	ds_bpermute_b32 v228, v231, v228
	ds_bpermute_b32 v229, v231, v229
	v_add_u32_e32 v4, v152, v230
	v_ashrrev_i32_e32 v5, 31, v4
	v_lshlrev_b64 v[2:3], 11, v[4:5]
	v_lshl_add_u64 v[2:3], s[70:71], 0, v[2:3]
	v_lshl_add_u64 v[2:3], v[2:3], 0, s[82:83]
	v_lshl_add_u64 v[2:3], v[2:3], 0, v[232:233]
	v_add_u32_e32 v6, 16, v4
	v_ashrrev_i32_e32 v7, 31, v6
	v_lshlrev_b64 v[6:7], 11, v[6:7]
	v_lshl_add_u64 v[6:7], s[70:71], 0, v[6:7]
	v_lshl_add_u64 v[6:7], v[6:7], 0, s[82:83]
	v_lshl_add_u64 v[6:7], v[6:7], 0, v[232:233]
	s_waitcnt lgkmcnt(0)
	global_store_dwordx2 v[2:3], v[214:215], off offset:512
	global_store_dwordx2 v[2:3], v[216:217], off offset:544
	global_store_dwordx2 v[2:3], v[218:219], off offset:576
	global_store_dwordx2 v[2:3], v[220:221], off offset:608
	global_store_dwordx2 v[6:7], v[222:223], off offset:512
	global_store_dwordx2 v[6:7], v[224:225], off offset:544
	global_store_dwordx2 v[6:7], v[226:227], off offset:576
	global_store_dwordx2 v[6:7], v[228:229], off offset:608
	s_barrier
	s_cbranch_scc1 .LBB0_97
.LBB0_101:
	v_readfirstlane_b32 s2, v140
	s_ashr_i32 s3, s2, 7
	s_and_b32 s22, s58, 1
	s_lshr_b32 s2, s2, 1
	s_lshl_b32 s10, s22, 6
	s_and_b32 s2, s2, 32
	s_or_b32 s26, s2, s10
	s_ashr_i32 s2, s58, 2
	s_bfe_u32 s28, s58, 0x10001
	s_lshl_b32 s10, s28, 2
	s_lshl_b32 s29, s2, 7
	s_add_i32 s74, s3, s10
	s_ashr_i32 s99, s74, 31
	s_mov_b32 s98, s74
	s_lshl_b64 s[98:99], s[98:99], 2
	s_add_u32 s98, s56, s98
	s_addc_u32 s99, s57, s99
	global_load_dword v213, v1, s[98:99]
	v_or_b32_e32 v0, s29, v145
	v_or_b32_e32 v152, s26, v0
	s_lshl_b32 s10, s74, 6
	s_ashr_i32 s11, s10, 31
	v_mov_b64_e32 v[2:3], s[72:73]
	v_or_b32_e32 v150, 16, v152
	v_mad_i64_i32 v[4:5], s[20:21], v152, s64, v[2:3]
	s_lshl_b64 s[82:83], s[10:11], 1
	v_mad_i64_i32 v[2:3], s[10:11], v150, s64, v[2:3]
	v_lshl_add_u64 v[4:5], v[4:5], 0, s[82:83]
	v_lshlrev_b32_e32 v0, 1, v146
	v_lshl_add_u64 v[2:3], v[2:3], 0, s[82:83]
	s_nop 0
	v_lshl_add_u64 v[6:7], v[4:5], 0, v[0:1]
	s_nop 0
	v_lshl_add_u64 v[14:15], v[2:3], 0, v[0:1]
	global_load_dwordx4 v[2:5], v[6:7], off offset:2048
	s_nop 0
	global_load_dwordx4 v[6:9], v[6:7], off offset:2112
	s_nop 0
	global_load_dwordx4 v[10:13], v[14:15], off offset:2048
	s_nop 0
	global_load_dwordx4 v[14:17], v[14:15], off offset:2112
	s_and_b32 s40, s2, 0x7f
	s_cmp_eq_u32 s40, 0
	s_cselect_b64 s[10:11], -1, 0
	s_add_i32 s3, s2, 0xffffff00
	s_ashr_i32 s16, s58, 9
	s_lshr_b32 s20, s3, 1
	s_cmpk_lt_i32 s2, 0x100
	s_cselect_b64 s[78:79], -1, 0
	v_cndmask_b32_e64 v0, 0, 1, s[10:11]
	s_and_b64 s[2:3], s[78:79], exec
	s_cselect_b32 s2, s16, s20
	v_readfirstlane_b32 s21, v0
	s_cselect_b32 s20, s21, 3
	s_lshl_b32 s23, s2, 8
	s_addk_i32 s23, 0x7e80
	v_ashrrev_i32_e32 v153, 31, v152
	v_ashrrev_i32_e32 v151, 31, v150
	s_cmp_lt_i32 s20, 1
	s_cbranch_scc1 .LBB0_106
	s_cmp_lg_u32 s20, 1
	s_mov_b64 s[2:3], -1
	s_cbranch_scc0 .LBB0_104
	s_lshl_b32 s2, s20, 7
	s_add_i32 s16, s23, s2
	s_mov_b64 s[2:3], 0
